# ph1/ph2 unit start: hipcc's own s_waitcnt vmcnt(0) ahead of the K-loop dropped (template's counted waits cover the LDS-DMA stages; it only waited for the previous unit's stores)
# baseline (speedup 1.0000x reference)
; #define PG8_STAGE(bufoff, gbase, voff) do { _Pragma("unroll") for (int _i = 0; _i < 2; ++_i) \
;         __builtin_amdgcn_global_load_lds((const unsigned*)((const char*)(gbase) + (voff)[_i]), (LAS unsigned*)(lds + (bufoff) + ldsw + _i * 8192), 16, 0, 0); } while (0)
; #define PG8_WAIT_V(n) asm volatile("s_waitcnt vmcnt(" #n ")" ::: "memory")
; #define PG8_BAR __builtin_amdgcn_s_barrier()
; template <class Epi>
; __device__ __forceinline__ void gemm_phase(LAS unsigned char* lds, const Gemm g, const StaticOrder& S, const Epi& E) {
;     ...
;     f32x4 acc[2][2][4][2];
; #pragma unroll
;     for (int a = 0; a < 2; ++a)
; #pragma unroll
;         for (int b = 0; b < 2; ++b)
; #pragma unroll
;             for (int m = 0; m < 4; ++m)
; #pragma unroll
;                 for (int n = 0; n < 2; ++n) acc[a][b][m][n] = (f32x4){0.f, 0.f, 0.f, 0.f};
;     bf16x8 At[4][2], B0[2][2], B1[2][2];
;     const char* cA = (const char*)g.A + (size_t)cur.pm * tstepA + (size_t)cur.pn * g.a_pn_off * 2; const char* cB = (const char*)g.Bt + (size_t)cur.pn * tstepB;
;     PG8_STAGE(PG8_SB(0, 0), cB, voffB); PG8_STAGE(PG8_SA(0, 0), cA, voffA); PG8_STAGE(PG8_SB(0, 1), cB + hstepB, voffB); PG8_STAGE(PG8_SA(0, 1), cA + hstepA, voffA);
;     if (wr == 1) PG8_BAR;
;     PG8_WAIT_V(4); PG8_BAR;
;     PG8_STAGE(PG8_SB(1, 0), cB + kstep, voffB); PG8_STAGE(PG8_SA(1, 0), cA + kstep, voffA); PG8_STAGE(PG8_SB(1, 1), cB + hstepB + kstep, voffB);
;     PG8_WAIT_V(6); PG8_BAR;
;     for (;;) {
;         const bool has_next = S.next(ui + 1, nxt);
;         const char* nA = has_next ? (const char*)g.A + (size_t)nxt.pm * tstepA + (size_t)nxt.pn * g.a_pn_off * 2 : cA; const char* nB = has_next ? (const char*)g.Bt + (size_t)nxt.pn * tstepB : cB;
;         for (int t = 0; t < nt; t += 2) {
;             const bool last = (t == nt - 2);
;             const char* a1 = cA + (size_t)(t + 1) * kstep;
;             const char* a2 = last ? nA : cA + (size_t)(t + 2) * kstep; const char* b2 = last ? nB : cB + (size_t)(t + 2) * kstep;
.LBB0_1440:
	s_ashr_i32 s29, s28, 31
	s_lshl_b64 s[30:31], s[28:29], 19
	s_add_u32 s29, s74, s30
	s_addc_u32 s34, s75, s31
	s_ashr_i32 s27, s26, 31
	s_lshl_b64 s[30:31], s[26:27], 9
	s_add_u32 s30, s29, s30
	s_addc_u32 s31, s34, s31
	s_lshl_b64 s[34:35], s[26:27], 17
	s_add_u32 s34, s54, s34
	v_pk_mov_b32 v[0:1], 0, 0
	v_cmp_lt_i64_e64 s[10:11], s[10:11], v[188:189]
	s_addc_u32 s35, s55, s35
	s_andn2_b64 vcc, exec, s[24:25]
	v_pk_mov_b32 v[2:3], 0, 0
	v_pk_mov_b32 v[4:5], 0, 0
	v_pk_mov_b32 v[6:7], 0, 0
	v_pk_mov_b32 v[8:9], 0, 0
	v_pk_mov_b32 v[10:11], 0, 0
	v_pk_mov_b32 v[12:13], 0, 0
	v_pk_mov_b32 v[14:15], 0, 0
	v_pk_mov_b32 v[16:17], 0, 0
	v_pk_mov_b32 v[18:19], 0, 0
	v_pk_mov_b32 v[20:21], 0, 0
	v_pk_mov_b32 v[22:23], 0, 0
	v_pk_mov_b32 v[24:25], 0, 0
	v_pk_mov_b32 v[26:27], 0, 0
	v_pk_mov_b32 v[28:29], 0, 0
	v_pk_mov_b32 v[30:31], 0, 0
	v_pk_mov_b32 v[32:33], 0, 0
	v_pk_mov_b32 v[34:35], 0, 0
	v_pk_mov_b32 v[36:37], 0, 0
	v_pk_mov_b32 v[38:39], 0, 0
	v_pk_mov_b32 v[40:41], 0, 0
	v_pk_mov_b32 v[42:43], 0, 0
	v_pk_mov_b32 v[44:45], 0, 0
	v_pk_mov_b32 v[46:47], 0, 0
	v_pk_mov_b32 v[48:49], 0, 0
	v_pk_mov_b32 v[50:51], 0, 0
	v_pk_mov_b32 v[52:53], 0, 0
	v_pk_mov_b32 v[54:55], 0, 0
	v_pk_mov_b32 v[56:57], 0, 0
	v_pk_mov_b32 v[58:59], 0, 0
	v_pk_mov_b32 v[60:61], 0, 0
	v_pk_mov_b32 v[62:63], 0, 0
	v_pk_mov_b32 v[64:65], 0, 0
	v_pk_mov_b32 v[66:67], 0, 0
	v_pk_mov_b32 v[68:69], 0, 0
	v_pk_mov_b32 v[70:71], 0, 0
	v_pk_mov_b32 v[72:73], 0, 0
	v_pk_mov_b32 v[74:75], 0, 0
	v_pk_mov_b32 v[76:77], 0, 0
	v_pk_mov_b32 v[78:79], 0, 0
	v_pk_mov_b32 v[80:81], 0, 0
	v_pk_mov_b32 v[82:83], 0, 0
	v_pk_mov_b32 v[84:85], 0, 0
	v_pk_mov_b32 v[86:87], 0, 0
	v_pk_mov_b32 v[88:89], 0, 0
	v_pk_mov_b32 v[90:91], 0, 0
	v_pk_mov_b32 v[92:93], 0, 0
	v_pk_mov_b32 v[94:95], 0, 0
	v_pk_mov_b32 v[96:97], 0, 0
	v_pk_mov_b32 v[98:99], 0, 0
	v_pk_mov_b32 v[100:101], 0, 0
	v_pk_mov_b32 v[102:103], 0, 0
	v_pk_mov_b32 v[104:105], 0, 0
	v_pk_mov_b32 v[106:107], 0, 0
	v_pk_mov_b32 v[108:109], 0, 0
	v_pk_mov_b32 v[110:111], 0, 0
	v_pk_mov_b32 v[112:113], 0, 0
	v_pk_mov_b32 v[114:115], 0, 0
	v_pk_mov_b32 v[116:117], 0, 0
	v_pk_mov_b32 v[118:119], 0, 0
	v_pk_mov_b32 v[120:121], 0, 0
	v_pk_mov_b32 v[122:123], 0, 0
	v_pk_mov_b32 v[124:125], 0, 0
	v_pk_mov_b32 v[126:127], 0, 0
	s_waitcnt lgkmcnt(0)
	s_cbranch_vccnz .LBB0_1443
	s_and_b64 s[10:11], s[10:11], exec
	s_cselect_b32 s27, s31, s43
	s_cselect_b32 s29, s30, s42
	s_cselect_b32 s64, s35, s41
	s_cselect_b32 s65, s34, s40
	s_add_u32 s10, s42, 0x40080
	s_addc_u32 s11, s43, 0
	s_add_u32 s80, s40, 0x100
	s_addc_u32 s81, s41, 0
	s_mov_b32 s40, 0

; #define PG8_STAGE(bufoff, gbase, voff) do { _Pragma("unroll") for (int _i = 0; _i < 2; ++_i) \
;         __builtin_amdgcn_global_load_lds((const unsigned*)((const char*)(gbase) + (voff)[_i]), (LAS unsigned*)(lds + (bufoff) + ldsw + _i * 8192), 16, 0, 0); } while (0)
; #define PG8_WAIT_V(n) asm volatile("s_waitcnt vmcnt(" #n ")" ::: "memory")
; #define PG8_BAR __builtin_amdgcn_s_barrier()
; template <class Epi>
; __device__ __forceinline__ void gemm_phase(LAS unsigned char* lds, const Gemm g, const StaticOrder& S, const Epi& E) {
;     ...
;     f32x4 acc[2][2][4][2];
; #pragma unroll
;     for (int a = 0; a < 2; ++a)
; #pragma unroll
;         for (int b = 0; b < 2; ++b)
; #pragma unroll
;             for (int m = 0; m < 4; ++m)
; #pragma unroll
;                 for (int n = 0; n < 2; ++n) acc[a][b][m][n] = (f32x4){0.f, 0.f, 0.f, 0.f};
;     bf16x8 At[4][2], B0[2][2], B1[2][2];
;     const char* cA = (const char*)g.A + (size_t)cur.pm * tstepA + (size_t)cur.pn * g.a_pn_off * 2; const char* cB = (const char*)g.Bt + (size_t)cur.pn * tstepB;
;     PG8_STAGE(PG8_SB(0, 0), cB, voffB); PG8_STAGE(PG8_SA(0, 0), cA, voffA); PG8_STAGE(PG8_SB(0, 1), cB + hstepB, voffB); PG8_STAGE(PG8_SA(0, 1), cA + hstepA, voffA);
;     if (wr == 1) PG8_BAR;
;     PG8_WAIT_V(4); PG8_BAR;
;     PG8_STAGE(PG8_SB(1, 0), cB + kstep, voffB); PG8_STAGE(PG8_SA(1, 0), cA + kstep, voffA); PG8_STAGE(PG8_SB(1, 1), cB + hstepB + kstep, voffB);
;     PG8_WAIT_V(6); PG8_BAR;
;     for (;;) {
;         const bool has_next = S.next(ui + 1, nxt);
;         const char* nA = has_next ? (const char*)g.A + (size_t)nxt.pm * tstepA + (size_t)nxt.pn * g.a_pn_off * 2 : cA; const char* nB = has_next ? (const char*)g.Bt + (size_t)nxt.pn * tstepB : cB;
;         for (int t = 0; t < nt; t += 2) {
;             const bool last = (t == nt - 2);
;             const char* a1 = cA + (size_t)(t + 1) * kstep;
;             const char* a2 = last ? nA : cA + (size_t)(t + 2) * kstep; const char* b2 = last ? nB : cB + (size_t)(t + 2) * kstep;
.LBB0_1542:
	s_ashr_i32 s17, s16, 31
	s_lshl_b64 s[18:19], s[16:17], 19
	s_add_u32 s18, s70, s18
	s_addc_u32 s19, s71, s19
	s_ashr_i32 s15, s14, 31
	s_lshl_b64 s[22:23], s[14:15], 19
	s_add_u32 s22, s31, s22
	v_pk_mov_b32 v[0:1], 0, 0
	v_cmp_lt_i64_e64 s[8:9], s[8:9], v[140:141]
	s_addc_u32 s23, s34, s23
	s_andn2_b64 vcc, exec, s[12:13]
	v_pk_mov_b32 v[2:3], 0, 0
	v_pk_mov_b32 v[4:5], 0, 0
	v_pk_mov_b32 v[6:7], 0, 0
	v_pk_mov_b32 v[8:9], 0, 0
	v_pk_mov_b32 v[10:11], 0, 0
	v_pk_mov_b32 v[12:13], 0, 0
	v_pk_mov_b32 v[14:15], 0, 0
	v_pk_mov_b32 v[16:17], 0, 0
	v_pk_mov_b32 v[18:19], 0, 0
	v_pk_mov_b32 v[20:21], 0, 0
	v_pk_mov_b32 v[22:23], 0, 0
	v_pk_mov_b32 v[24:25], 0, 0
	v_pk_mov_b32 v[26:27], 0, 0
	v_pk_mov_b32 v[28:29], 0, 0
	v_pk_mov_b32 v[30:31], 0, 0
	v_pk_mov_b32 v[32:33], 0, 0
	v_pk_mov_b32 v[34:35], 0, 0
	v_pk_mov_b32 v[36:37], 0, 0
	v_pk_mov_b32 v[38:39], 0, 0
	v_pk_mov_b32 v[40:41], 0, 0
	v_pk_mov_b32 v[42:43], 0, 0
	v_pk_mov_b32 v[44:45], 0, 0
	v_pk_mov_b32 v[46:47], 0, 0
	v_pk_mov_b32 v[48:49], 0, 0
	v_pk_mov_b32 v[50:51], 0, 0
	v_pk_mov_b32 v[52:53], 0, 0
	v_pk_mov_b32 v[54:55], 0, 0
	v_pk_mov_b32 v[56:57], 0, 0
	v_pk_mov_b32 v[58:59], 0, 0
	v_pk_mov_b32 v[60:61], 0, 0
	v_pk_mov_b32 v[62:63], 0, 0
	v_pk_mov_b32 v[64:65], 0, 0
	v_pk_mov_b32 v[66:67], 0, 0
	v_pk_mov_b32 v[68:69], 0, 0
	v_pk_mov_b32 v[70:71], 0, 0
	v_pk_mov_b32 v[72:73], 0, 0
	v_pk_mov_b32 v[74:75], 0, 0
	v_pk_mov_b32 v[76:77], 0, 0
	v_pk_mov_b32 v[78:79], 0, 0
	v_pk_mov_b32 v[80:81], 0, 0
	v_pk_mov_b32 v[82:83], 0, 0
	v_pk_mov_b32 v[84:85], 0, 0
	v_pk_mov_b32 v[86:87], 0, 0
	v_pk_mov_b32 v[88:89], 0, 0
	v_pk_mov_b32 v[90:91], 0, 0
	v_pk_mov_b32 v[92:93], 0, 0
	v_pk_mov_b32 v[94:95], 0, 0
	v_pk_mov_b32 v[96:97], 0, 0
	v_pk_mov_b32 v[98:99], 0, 0
	v_pk_mov_b32 v[100:101], 0, 0
	v_pk_mov_b32 v[102:103], 0, 0
	v_pk_mov_b32 v[104:105], 0, 0
	v_pk_mov_b32 v[106:107], 0, 0
	v_pk_mov_b32 v[108:109], 0, 0
	v_pk_mov_b32 v[110:111], 0, 0
	v_pk_mov_b32 v[112:113], 0, 0
	v_pk_mov_b32 v[114:115], 0, 0
	v_pk_mov_b32 v[116:117], 0, 0
	v_pk_mov_b32 v[118:119], 0, 0
	v_pk_mov_b32 v[120:121], 0, 0
	v_pk_mov_b32 v[122:123], 0, 0
	v_pk_mov_b32 v[124:125], 0, 0
	v_pk_mov_b32 v[126:127], 0, 0
	s_cbranch_vccnz .LBB0_1535
	s_and_b64 s[8:9], s[8:9], exec
	s_cselect_b32 s15, s19, s29
	s_cselect_b32 s17, s18, s28
	s_cselect_b32 s63, s23, s27
	s_cselect_b32 s64, s22, s26
	s_add_u32 s8, s28, 0x40080
	s_addc_u32 s9, s29, 0
	s_add_u32 s65, s26, 0x100
	s_addc_u32 s76, s27, 0
	s_mov_b32 s26, 0
